# attention: unmasked fast path for the next-round V prefetch when the window is fully in range (12 loads off running bases)
# speedup vs baseline: 1.0085x; 1.0033x over previous
; #define ATT_LOADK(buf, grp) do { _Pragma("unroll") for (int tt = 0; tt < 3; ++tt) { int ki = kbase + 16 * ((grp) * 3 + tt); ki = ki < 0 ? 0 : (ki > a.m - 1 ? a.m - 1 : ki); \
;             const bf16_t* kp = kcol + (size_t)ki * 128; \
;             _Pragma("unroll") for (int ks = 0; ks < 4; ++ks) Kf[buf][tt][ks] = *(const bf16x8*)(kp + 32 * ks); } } while (0)
; #define ATT_MMAK(buf, grp) do { _Pragma("unroll") for (int tt = 0; tt < 3; ++tt) { f32x4 acc_ = (f32x4){0.f, 0.f, 0.f, 0.f}; \
;             _Pragma("unroll") for (int ks = 0; ks < 4; ++ks) acc_ = __builtin_amdgcn_mfma_f32_16x16x32_bf16(Kf[buf][tt][ks], Qf[ks], acc_, 0, 0, 0); sa[(grp) * 3 + tt] = acc_; } } while (0)
; __device__ __forceinline__ void attn_phase(LAS unsigned char* lds, bf16_t* qkv, float* lse, const float* biasT, int G) {
;     ...
;         const size_t tokq = (size_t)(a.pos0 + a.r + ((16 * w4 + li) << a.dsh));
;         const int pbase = a.seq_base + a.r * a.m;
;         bf16_t* qp = qkv + ((size_t)a.head * M_TOK + pbase + a.i0 + 16 * w4 + li) * 128;
;         bf16x8 Qf[4];
; #pragma unroll
;         for (int ks = 0; ks < 4; ++ks) Qf[ks] = *(const bf16x8*)(qp + 32 * ks + 8 * lg);
;         const int kbase = a.i0 - 64 + 16 * w4 + li;
;         const bf16_t* kcol = qkv + ((size_t)(12 + a.head) * M_TOK + pbase) * 128 + 8 * lg;
;         f32x4 sa[10];
;         bf16x8 Kf[2][3][4];
;     ...
;         ATT_LOADK(0, 0); ATT_LOADK(1, 1);
;         __builtin_amdgcn_sched_barrier(0);
;         ATT_MMAK(0, 0);
;         __builtin_amdgcn_sched_barrier(0);
;         ATT_LOADK(0, 2);
;         if (pairn < 4608) { const AttnItem an = attn_item(pairn * 2 + half); attn_load_v(an, qkv, ht, vreg); }
.LBB0_425:
	s_or_b64 exec, exec, s[0:1]
	s_mul_i32 s0, s10, 0xfffffd00
	s_add_i32 s0, s0, s9
	s_lshl_b32 s1, s0, 6
	s_and_b32 s9, s1, 0xffffe000
	s_cmpk_lt_i32 s0, 0x200
	s_cselect_b32 s0, 13, 14
	s_cselect_b32 s9, s9, 0x8000
	s_ashr_i32 s11, s10, 1
	s_and_b32 s12, s11, -2
	s_sub_i32 s11, s0, s12
	s_sub_i32 s30, s1, s9
	s_ashr_i32 s96, s30, s11
	s_lshl_b32 s31, s96, s11
	s_sub_i32 s13, s30, s31
	s_add_i32 s16, s31, s9
	s_mul_hi_i32 s0, s10, 0xc000
	s_ashr_i32 s18, s16, 31
	s_ashr_i32 s1, s13, 31
	s_mul_i32 s17, s10, 0xc000
	v_mov_b32_e32 v3, s0
	s_add_u32 s0, s13, s16
	v_or_b32_e32 v2, s17, v184
	s_addc_u32 s1, s1, s18
	v_lshl_add_u64 v[2:3], s[0:1], 0, v[2:3]
	v_readlane_b32 s0, v250, 21
	s_add_i32 s15, s13, s0
	s_add_i32 s0, s10, 12
	s_add_i32 s17, s17, 0x90000
	v_lshlrev_b64 v[2:3], 8, v[2:3]
	s_mul_hi_i32 s1, s0, 0xc000
	s_add_u32 s0, s17, s16
	v_lshl_add_u64 v[194:195], s[92:93], 0, v[2:3]
	v_mov_b32_e32 v191, v1
	s_addc_u32 s1, s1, s18
	v_lshl_add_u64 v[2:3], v[194:195], 0, v[190:191]
	s_lshl_b64 s[0:1], s[0:1], 8
	global_load_dwordx4 v[96:99], v[2:3], off
	global_load_dwordx4 v[92:95], v[2:3], off offset:64
	global_load_dwordx4 v[88:91], v[2:3], off offset:128
	global_load_dwordx4 v[52:55], v[2:3], off offset:192
	v_add_u32_e32 v0, s15, v216
	v_lshl_add_u64 v[2:3], v[186:187], 0, s[0:1]
	s_bfm_b32 s0, s11, 0
	v_min_i32_e32 v56, s0, v0
	v_ashrrev_i32_e32 v57, 31, v56
	v_lshlrev_b64 v[56:57], 7, v[56:57]
	v_cmp_lt_i32_e32 vcc, -1, v0
	s_movk_i32 s1, 0xffef
	v_add_u32_e32 v58, 48, v0
	v_cndmask_b32_e32 v57, 0, v57, vcc
	v_cndmask_b32_e32 v56, 0, v56, vcc
	v_lshl_add_u64 v[56:57], v[56:57], 1, v[2:3]
	global_load_dwordx4 v[68:71], v[56:57], off
	global_load_dwordx4 v[72:75], v[56:57], off offset:64
	global_load_dwordx4 v[80:83], v[56:57], off offset:128
	global_load_dwordx4 v[84:87], v[56:57], off offset:192
	v_add_u32_e32 v56, 16, v0
	v_min_i32_e32 v56, s0, v56
	v_ashrrev_i32_e32 v57, 31, v56
	v_lshlrev_b64 v[56:57], 7, v[56:57]
	v_cmp_lt_i32_e32 vcc, s1, v0
	s_movk_i32 s1, 0xffdf
	v_add_u32_e32 v102, 64, v0
	v_cndmask_b32_e32 v57, 0, v57, vcc
	v_cndmask_b32_e32 v56, 0, v56, vcc
	v_lshl_add_u64 v[56:57], v[56:57], 1, v[2:3]
	global_load_dwordx4 v[116:119], v[56:57], off
	global_load_dwordx4 v[136:139], v[56:57], off offset:64
	global_load_dwordx4 v[140:143], v[56:57], off offset:128
	global_load_dwordx4 v[144:147], v[56:57], off offset:192
	v_add_u32_e32 v56, 32, v0
	v_min_i32_e32 v56, s0, v56
	v_ashrrev_i32_e32 v57, 31, v56
	v_lshlrev_b64 v[56:57], 7, v[56:57]
	v_cmp_lt_i32_e32 vcc, s1, v0
	v_min_i32_e32 v100, s0, v102
	v_add_u32_e32 v122, 0x50, v0
	v_cndmask_b32_e32 v57, 0, v57, vcc
	v_cndmask_b32_e32 v56, 0, v56, vcc
	v_lshl_add_u64 v[56:57], v[56:57], 1, v[2:3]
	global_load_dwordx4 v[148:151], v[56:57], off
	global_load_dwordx4 v[152:155], v[56:57], off offset:64
	global_load_dwordx4 v[156:159], v[56:57], off offset:128
	global_load_dwordx4 v[160:163], v[56:57], off offset:192
	v_min_i32_e32 v56, s0, v58
	v_ashrrev_i32_e32 v57, 31, v56
	v_lshlrev_b64 v[56:57], 7, v[56:57]
	v_cmp_lt_i32_e32 vcc, -1, v58
	v_ashrrev_i32_e32 v101, 31, v100
	v_min_i32_e32 v120, s0, v122
	v_cndmask_b32_e32 v57, 0, v57, vcc
	v_cndmask_b32_e32 v56, 0, v56, vcc
	v_lshlrev_b64 v[100:101], 7, v[100:101]
	v_cmp_lt_i32_e32 vcc, -1, v102
	v_ashrrev_i32_e32 v121, 31, v120
	v_lshlrev_b64 v[120:121], 7, v[120:121]
	v_cndmask_b32_e32 v101, 0, v101, vcc
	v_cndmask_b32_e32 v100, 0, v100, vcc
	v_cmp_lt_i32_e32 vcc, -1, v122
	v_lshl_add_u64 v[76:77], v[56:57], 1, v[2:3]
	v_lshl_add_u64 v[112:113], v[100:101], 1, v[2:3]
	v_cndmask_b32_e32 v121, 0, v121, vcc
	v_cndmask_b32_e32 v120, 0, v120, vcc
	v_lshl_add_u64 v[132:133], v[120:121], 1, v[2:3]
	global_load_dwordx4 v[56:59], v[76:77], off
	global_load_dwordx4 v[60:63], v[76:77], off offset:64
	global_load_dwordx4 v[64:67], v[76:77], off offset:128
	s_nop 0
	global_load_dwordx4 v[76:79], v[76:77], off offset:192
	s_nop 0
	global_load_dwordx4 v[100:103], v[112:113], off
	global_load_dwordx4 v[104:107], v[112:113], off offset:64
	global_load_dwordx4 v[108:111], v[112:113], off offset:128
	s_nop 0
	global_load_dwordx4 v[112:115], v[112:113], off offset:192
	s_nop 0
	global_load_dwordx4 v[120:123], v[132:133], off
	global_load_dwordx4 v[124:127], v[132:133], off offset:64
	global_load_dwordx4 v[128:131], v[132:133], off offset:128
	s_nop 0
	global_load_dwordx4 v[132:135], v[132:133], off offset:192
	s_waitcnt vmcnt(23)
	v_mfma_f32_16x16x32_bf16 v[68:71], v[68:71], v[96:99], 0
	s_waitcnt vmcnt(22)
	v_mfma_f32_16x16x32_bf16 v[68:71], v[72:75], v[92:95], v[68:71]
	s_waitcnt vmcnt(21)
	v_mfma_f32_16x16x32_bf16 v[68:71], v[80:83], v[88:91], v[68:71]
	s_waitcnt vmcnt(20)
	v_mfma_f32_16x16x32_bf16 v[84:87], v[84:87], v[52:55], v[68:71]
	s_waitcnt vmcnt(19)
	v_mfma_f32_16x16x32_bf16 v[68:71], v[116:119], v[96:99], 0
	s_waitcnt vmcnt(18)
	v_mfma_f32_16x16x32_bf16 v[68:71], v[136:139], v[92:95], v[68:71]
	s_waitcnt vmcnt(17)
	v_mfma_f32_16x16x32_bf16 v[68:71], v[140:143], v[88:91], v[68:71]
	s_waitcnt vmcnt(16)
	v_mfma_f32_16x16x32_bf16 v[72:75], v[144:147], v[52:55], v[68:71]
	s_waitcnt vmcnt(15)
	v_mfma_f32_16x16x32_bf16 v[68:71], v[148:151], v[96:99], 0
	s_waitcnt vmcnt(14)
	v_mfma_f32_16x16x32_bf16 v[68:71], v[152:155], v[92:95], v[68:71]
	s_waitcnt vmcnt(13)
	v_mfma_f32_16x16x32_bf16 v[68:71], v[156:159], v[88:91], v[68:71]
	s_waitcnt vmcnt(12)
	v_mfma_f32_16x16x32_bf16 v[68:71], v[160:163], v[52:55], v[68:71]
	v_add_u32_e32 v82, 0x60, v0
	v_min_i32_e32 v80, s0, v82
	v_ashrrev_i32_e32 v81, 31, v80
	v_lshlrev_b64 v[80:81], 7, v[80:81]
	v_cmp_lt_i32_e32 vcc, -1, v82
	v_add_u32_e32 v82, 0x70, v0
	v_add_u32_e32 v0, 0x80, v0
	v_cndmask_b32_e32 v81, 0, v81, vcc
	v_cndmask_b32_e32 v80, 0, v80, vcc
	v_lshl_add_u64 v[80:81], v[80:81], 1, v[2:3]
	global_load_dwordx4 v[136:139], v[80:81], off
	global_load_dwordx4 v[140:143], v[80:81], off offset:64
	global_load_dwordx4 v[144:147], v[80:81], off offset:128
	global_load_dwordx4 v[148:151], v[80:81], off offset:192
	v_min_i32_e32 v80, s0, v82
	v_ashrrev_i32_e32 v81, 31, v80
	v_lshlrev_b64 v[80:81], 7, v[80:81]
	v_cmp_lt_i32_e32 vcc, -1, v82
	s_cmpk_gt_i32 s14, 0x11ff
	s_nop 0
	v_cndmask_b32_e32 v81, 0, v81, vcc
	v_cndmask_b32_e32 v80, 0, v80, vcc
	v_lshl_add_u64 v[80:81], v[80:81], 1, v[2:3]
	global_load_dwordx4 v[152:155], v[80:81], off
	global_load_dwordx4 v[156:159], v[80:81], off offset:64
	global_load_dwordx4 v[160:163], v[80:81], off offset:128
	global_load_dwordx4 v[164:167], v[80:81], off offset:192
	v_min_i32_e32 v80, s0, v0
	v_ashrrev_i32_e32 v81, 31, v80
	v_lshlrev_b64 v[80:81], 7, v[80:81]
	v_cmp_lt_i32_e32 vcc, -1, v0
	s_nop 1
	v_cndmask_b32_e32 v81, 0, v81, vcc
	v_cndmask_b32_e32 v80, 0, v80, vcc
	v_lshl_add_u64 v[2:3], v[80:81], 1, v[2:3]
	global_load_dwordx4 v[176:179], v[2:3], off
	global_load_dwordx4 v[172:175], v[2:3], off offset:64
	global_load_dwordx4 v[168:171], v[2:3], off offset:128
	global_load_dwordx4 v[116:119], v[2:3], off offset:192
	s_cbranch_scc1 .LBB0_451
; __device__ __forceinline__ void attn_load_v(const AttnItem& a, const bf16_t* qkv, int ht, u32x4 (&vreg)[12]) {
; #pragma unroll
;     for (int pass = 0; pass < 12; ++pass) {
;         const int row = pass * 16 + (ht >> 4), ch = ht & 15, ki = a.i0 - 64 + row;
;         u32x4 val = (u32x4){0u, 0u, 0u, 0u};
;         if (ki >= 0 && ki < a.m) val = *(const u32x4*)(qkv + ((size_t)(24 + a.head) * M_TOK + a.seq_base + a.r * a.m + ki) * 128 + ch * 8);
;         vreg[pass] = val;
;     }
; }
; __device__ __forceinline__ void attn_phase(LAS unsigned char* lds, bf16_t* qkv, float* lse, const float* biasT, int G) {
;     ...
;         if (pairn < 4608) { const AttnItem an = attn_item(pairn * 2 + half); attn_load_v(an, qkv, ht, vreg); }
	s_lshl_b32 s0, s14, 1
	s_add_i32 s0, s0, s94
	s_mul_hi_i32 s1, s0, 0x2aaaaaab
	s_lshr_b32 s14, s1, 31
	s_ashr_i32 s1, s1, 7
	s_add_i32 s14, s1, s14
	s_mul_i32 s1, s14, 0xfffffd00
	s_add_i32 s1, s1, s0
	s_lshl_b32 s0, s1, 6
	s_and_b32 s16, s0, 0xffffe000
	s_cmpk_lt_i32 s1, 0x200
	s_cselect_b32 s1, 13, 14
	s_cselect_b32 s16, s16, 0x8000
	s_ashr_i32 s17, s14, 1
	s_and_b32 s17, s17, -2
	s_sub_i32 s1, s1, s17
	s_lshl_b32 s18, 1, s1
	s_sub_i32 s0, s0, s16
	s_lshl_b32 s1, -1, s1
	s_and_b32 s17, s1, s0
	s_sub_i32 s19, s0, s17
	s_cmp_lt_i32 s19, 64
	s_cbranch_scc1 .Lattn_vslow
	s_add_i32 s0, s19, 0x80
	s_cmp_gt_i32 s0, s18
	s_cbranch_scc1 .Lattn_vslow
	s_add_i32 s28, s14, 24
	s_mul_i32 s28, s28, 0xc000
	s_add_i32 s28, s28, s16
	s_add_i32 s28, s28, s17
	s_add_i32 s28, s28, s19
	v_add_u32_e32 v0, s28, v220
	v_lshlrev_b32_e32 v0, 8, v0
	s_mov_b64 s[28:29], 0x1000
	v_lshl_add_u64 v[2:3], v[188:189], 0, v[0:1]
	v_lshl_add_u64 v[2:3], s[28:29], 0, v[2:3]
	s_mov_b64 s[28:29], 0x2000
	global_load_dwordx4 v[8:11], v[2:3], off offset:-4096
	global_load_dwordx4 v[4:7], v[2:3], off
	v_lshl_add_u64 v[2:3], s[28:29], 0, v[2:3]
	global_load_dwordx4 v[12:15], v[2:3], off offset:-4096
	global_load_dwordx4 v[16:19], v[2:3], off
	v_lshl_add_u64 v[2:3], s[28:29], 0, v[2:3]
	global_load_dwordx4 v[20:23], v[2:3], off offset:-4096
	global_load_dwordx4 v[24:27], v[2:3], off
	v_lshl_add_u64 v[2:3], s[28:29], 0, v[2:3]
	global_load_dwordx4 v[28:31], v[2:3], off offset:-4096
	global_load_dwordx4 v[32:35], v[2:3], off
	v_lshl_add_u64 v[2:3], s[28:29], 0, v[2:3]
	global_load_dwordx4 v[36:39], v[2:3], off offset:-4096
	global_load_dwordx4 v[40:43], v[2:3], off
	v_lshl_add_u64 v[2:3], s[28:29], 0, v[2:3]
	global_load_dwordx4 v[44:47], v[2:3], off offset:-4096
	global_load_dwordx4 v[48:51], v[2:3], off
	s_branch .LBB0_451
.Lattn_vslow:
	v_add_u32_e32 v0, s19, v220
	v_mov_b32_e32 v6, v1
	v_mov_b32_e32 v7, v1
	v_cmp_lt_i32_e32 vcc, -1, v0
	v_cmp_gt_i32_e64 s[0:1], s18, v0
	v_mov_b32_e32 v4, v1
	v_mov_b32_e32 v5, v1
	v_mov_b64_e32 v[10:11], v[6:7]
	s_and_b64 s[28:29], vcc, s[0:1]
	v_mov_b64_e32 v[8:9], v[4:5]
	s_and_saveexec_b64 s[0:1], s[28:29]
	s_cbranch_execz .LBB0_428
	s_add_i32 s28, s14, 24
	s_mul_hi_i32 s29, s28, 0xc000
	s_mul_i32 s28, s28, 0xc000
	s_ashr_i32 vcc_lo, s16, 31
	s_ashr_i32 vcc_hi, s17, 31
	s_add_u32 s28, s28, s16
	s_addc_u32 s29, s29, vcc_lo
	s_add_u32 s28, s28, s17
	s_addc_u32 s29, s29, vcc_hi
	v_lshl_add_u64 v[2:3], s[28:29], 0, v[0:1]
	v_lshlrev_b64 v[2:3], 8, v[2:3]
	v_lshl_add_u64 v[2:3], v[188:189], 0, v[2:3]
	global_load_dwordx4 v[8:11], v[2:3], off

; template <bool COOP>
; __global__ void __launch_bounds__(512, 2) fwd_kernel(Params p) {
;     ...
;     }
; }
.LBB0_641:
	s_nop 0
	s_nop 0
	s_nop 0
	s_nop 0
	s_nop 0
	s_nop 0
	s_nop 0
	s_nop 0
	s_nop 0
	s_nop 0
	s_nop 0
	s_nop 0
	s_nop 0
	s_nop 0
	s_nop 0
	s_nop 0
	s_nop 0
	s_nop 0
	s_nop 0
	s_nop 0
	s_nop 0
	s_nop 0
	s_nop 0
	s_nop 0
	s_nop 0
	s_nop 0
	s_nop 0
	s_nop 0
	s_nop 0
	s_nop 0
	s_nop 0
	s_nop 0
	s_nop 0
	s_nop 0
	s_nop 0
	s_nop 0
	s_nop 0
	s_nop 0
	s_nop 0
	s_nop 0
	s_nop 0
	s_nop 0
	s_nop 0
	s_nop 0
	s_nop 0
	s_nop 0
	s_nop 0
	s_nop 0
	s_nop 0
	s_nop 0
	s_nop 0
	s_nop 0
	s_nop 0
	s_nop 0
	s_nop 0
	s_nop 0
	s_nop 0
	s_nop 0
	s_nop 0
	s_nop 0
	s_nop 0
	s_nop 0
	s_nop 0
	s_nop 0
	s_nop 0
	s_nop 0
	s_nop 0
	s_nop 0
	s_nop 0
	s_nop 0
	s_nop 0
	s_nop 0
	s_nop 0
	s_nop 0
	s_nop 0
	s_nop 0
	s_nop 0
	s_nop 0
	s_nop 0
	s_nop 0
	s_nop 0
	s_nop 0
	s_nop 0
	s_nop 0
	s_nop 0
	s_nop 0
	s_nop 0
	s_nop 0
	s_nop 0
	s_nop 0
	s_nop 0
	s_nop 0
	s_nop 0
	s_nop 0
	s_nop 0
	s_nop 0
	s_nop 0
	s_nop 0
	s_nop 0
	s_nop 0
	s_nop 0
	s_nop 0
	s_nop 0
	s_nop 0
	s_nop 0
	s_nop 0
	s_nop 0
	s_nop 0
	s_nop 0
	s_nop 0
	s_nop 0
	s_nop 0
	s_nop 0
	s_nop 0
	s_nop 0
	s_nop 0
	s_nop 0
	s_nop 0
	s_nop 0
	s_nop 0
	s_nop 0
	s_nop 0
	s_nop 0
	s_nop 0
	s_nop 0
	s_nop 0
	s_nop 0
	s_nop 0
	s_nop 0
	s_nop 0
	s_nop 0
	s_nop 0
	s_endpgm
